# phase 0: silu(c) staging with 16 loads in flight per pass (was one load per wait) + hand-scheduled adaLN GEMV inner loop (batched LDS reads, row_bcast reductions)
# speedup vs baseline: 1.0678x; 1.0100x over previous
.LBB0_121:
	s_add_i32 m0, s3, 0x18000
	v_lshl_add_u64 v[10:11], v[10:11], 0, s[4:5]
	s_waitcnt vmcnt(2)
	s_barrier
	global_load_lds_dwordx4 v[10:11], off
	v_lshl_add_u64 v[6:7], v[6:7], 0, s[4:5]
	s_add_i32 m0, s3, 0x1a000
	s_add_i32 s80, s3, 0x8000
	global_load_lds_dwordx4 v[6:7], off
	v_lshl_add_u64 v[6:7], v[8:9], 0, s[4:5]
	s_mov_b32 m0, s80
	s_add_i32 s84, s3, 0xa000
	global_load_lds_dwordx4 v[6:7], off
	v_lshl_add_u64 v[6:7], v[12:13], 0, s[4:5]
	s_mov_b32 m0, s84
	v_lshl_add_u64 v[4:5], v[4:5], 0, s[4:5]
	global_load_lds_dwordx4 v[6:7], off
	s_add_i32 m0, s3, 0x1c000
	v_lshl_add_u64 v[2:3], v[2:3], 0, s[4:5]
	global_load_lds_dwordx4 v[4:5], off
	s_add_i32 m0, s3, 0x1e000
	s_lshl_b32 s11, s11, 5
	global_load_lds_dwordx4 v[2:3], off
	v_lshrrev_b32_e32 v2, 1, v15
	v_and_b32_e32 v2, 24, v2
	s_and_b32 s34, s11, 0x60
	v_and_b32_e32 v1, 15, v15
	v_lshlrev_b32_e32 v3, 1, v2
	v_or_b32_e32 v172, s34, v2
	v_rcp_iflag_f32_e32 v2, v14
	v_lshlrev_b32_e32 v241, 2, v1
	s_lshr_b32 s83, s10, 6
	v_lshl_or_b32 v3, v1, 6, v3
	v_and_b32_e32 v4, 32, v241
	s_mov_b32 s100, 0x14000
	s_mov_b32 s11, 7
	s_cmp_eq_u32 s81, 0
	s_cbranch_scc1 .Lfl_remap
	s_branch .Lfl_noremap
.Lfl_remap:
	s_mov_b32 s100, 0x11000
	s_mov_b32 s11, 8

.LBB0_131:
	s_add_i32 s74, s44, 2
	s_add_u32 s75, s38, 0x80
	s_addc_u32 s45, s39, 0
	s_add_i32 s94, 0, 0x10000
	s_cmp_eq_u32 s11, s44
	s_cselect_b32 s45, s93, s45
	s_cselect_b32 s44, s92, s75
	s_cselect_b32 s89, s99, s57
	s_cselect_b32 s88, s98, s56
	s_add_i32 s75, 0, 0x14000
	v_add_u32_e32 v142, s94, v242
	v_add_u32_e32 v158, s100, v242
	ds_read_b128 v[130:133], v142
	ds_read_b128 v[134:137], v142 offset:1024
	ds_read_b128 v[138:141], v142 offset:2048
	ds_read_b128 v[142:145], v142 offset:3072
	ds_read_b128 v[146:149], v158
	ds_read_b128 v[150:153], v158 offset:1024
	ds_read_b128 v[154:157], v158 offset:2048
	ds_read_b128 v[158:161], v158 offset:3072
	v_lshl_add_u64 v[212:213], s[38:39], 0, v[176:177]
	s_add_i32 m0, s3, 0xc000
	ds_read_b128 v[180:183], v243
	ds_read_b128 v[184:187], v243 offset:1024
	ds_read_b128 v[188:191], v243 offset:2048
	ds_read_b128 v[192:195], v243 offset:3072
	ds_read_b128 v[196:199], v243 offset:4096
	ds_read_b128 v[200:203], v243 offset:5120
	ds_read_b128 v[204:207], v243 offset:6144
	ds_read_b128 v[208:211], v243 offset:7168
	global_load_lds_dwordx4 v[212:213], off
	v_lshl_add_u64 v[212:213], s[38:39], 0, v[178:179]
	s_add_i32 m0, s3, 0xe000
	s_nop 0
	global_load_lds_dwordx4 v[212:213], off
	s_waitcnt vmcnt(8)
	s_waitcnt lgkmcnt(0)
	s_barrier
	s_setprio 1
	s_waitcnt lgkmcnt(0)
	v_mfma_f32_16x16x32_bf16 v[126:129], v[130:133], v[180:183], v[126:129]
	v_mfma_f32_16x16x32_bf16 v[122:125], v[138:141], v[180:183], v[122:125]
	v_mfma_f32_16x16x32_bf16 v[110:113], v[130:133], v[188:191], v[110:113]
	v_mfma_f32_16x16x32_bf16 v[106:109], v[138:141], v[188:191], v[106:109]
	v_mfma_f32_16x16x32_bf16 v[94:97], v[130:133], v[196:199], v[94:97]
	v_mfma_f32_16x16x32_bf16 v[90:93], v[138:141], v[196:199], v[90:93]
	v_mfma_f32_16x16x32_bf16 v[78:81], v[130:133], v[204:207], v[78:81]
	v_mfma_f32_16x16x32_bf16 v[74:77], v[138:141], v[204:207], v[74:77]
	v_mfma_f32_16x16x32_bf16 v[126:129], v[134:137], v[184:187], v[126:129]
	v_mfma_f32_16x16x32_bf16 v[122:125], v[142:145], v[184:187], v[122:125]
	v_mfma_f32_16x16x32_bf16 v[110:113], v[134:137], v[192:195], v[110:113]
	v_mfma_f32_16x16x32_bf16 v[106:109], v[142:145], v[192:195], v[106:109]
	v_mfma_f32_16x16x32_bf16 v[94:97], v[134:137], v[200:203], v[94:97]
	v_mfma_f32_16x16x32_bf16 v[90:93], v[142:145], v[200:203], v[90:93]
	v_mfma_f32_16x16x32_bf16 v[78:81], v[134:137], v[208:211], v[78:81]
	v_mfma_f32_16x16x32_bf16 v[74:77], v[142:145], v[208:211], v[74:77]
	s_setprio 0
	s_setprio 1
	v_mfma_f32_16x16x32_bf16 v[118:121], v[146:149], v[180:183], v[118:121]
	v_mfma_f32_16x16x32_bf16 v[114:117], v[154:157], v[180:183], v[114:117]
	v_mfma_f32_16x16x32_bf16 v[102:105], v[146:149], v[188:191], v[102:105]
	v_mfma_f32_16x16x32_bf16 v[98:101], v[154:157], v[188:191], v[98:101]
	v_mfma_f32_16x16x32_bf16 v[86:89], v[146:149], v[196:199], v[86:89]
	v_mfma_f32_16x16x32_bf16 v[82:85], v[154:157], v[196:199], v[82:85]
	v_mfma_f32_16x16x32_bf16 v[70:73], v[146:149], v[204:207], v[70:73]
	v_mfma_f32_16x16x32_bf16 v[66:69], v[154:157], v[204:207], v[66:69]
	v_mfma_f32_16x16x32_bf16 v[118:121], v[150:153], v[184:187], v[118:121]
	v_mfma_f32_16x16x32_bf16 v[114:117], v[158:161], v[184:187], v[114:117]
	v_mfma_f32_16x16x32_bf16 v[102:105], v[150:153], v[192:195], v[102:105]
	v_mfma_f32_16x16x32_bf16 v[98:101], v[158:161], v[192:195], v[98:101]
	v_mfma_f32_16x16x32_bf16 v[86:89], v[150:153], v[200:203], v[86:89]
	v_mfma_f32_16x16x32_bf16 v[82:85], v[158:161], v[200:203], v[82:85]
	v_mfma_f32_16x16x32_bf16 v[70:73], v[150:153], v[208:211], v[70:73]
	v_mfma_f32_16x16x32_bf16 v[66:69], v[158:161], v[208:211], v[66:69]
	s_setprio 0
	s_barrier
	s_add_i32 s94, s94, s77
	v_lshl_add_u64 v[212:213], s[88:89], 0, v[166:167]
	s_mov_b32 m0, s94
	ds_read_b128 v[180:183], v243 offset:16384
	ds_read_b128 v[184:187], v243 offset:17408
	ds_read_b128 v[188:191], v243 offset:18432
	ds_read_b128 v[192:195], v243 offset:19456
	ds_read_b128 v[196:199], v243 offset:20480
	ds_read_b128 v[200:203], v243 offset:21504
	ds_read_b128 v[204:207], v243 offset:22528
	ds_read_b128 v[208:211], v243 offset:23552
	global_load_lds_dwordx4 v[212:213], off
	s_add_i32 m0, s94, 0x2000
	v_lshl_add_u64 v[214:215], s[88:89], 0, v[170:171]
	s_add_u32 s88, s88, s96
	s_addc_u32 s89, s89, 0
	s_add_i32 s75, s75, s77
	global_load_lds_dwordx4 v[214:215], off
	v_lshl_add_u64 v[216:217], s[88:89], 0, v[166:167]
	s_mov_b32 m0, s75
	v_lshl_add_u64 v[218:219], s[88:89], 0, v[170:171]
	global_load_lds_dwordx4 v[216:217], off
	s_add_i32 m0, s75, 0x2000
	v_lshl_add_u64 v[220:221], s[44:45], 0, v[164:165]
	global_load_lds_dwordx4 v[218:219], off
	s_mov_b32 m0, s3
	v_lshl_add_u64 v[222:223], s[44:45], 0, v[168:169]
	global_load_lds_dwordx4 v[220:221], off
	s_mov_b32 m0, s78
	s_nop 0
	global_load_lds_dwordx4 v[222:223], off
	s_waitcnt vmcnt(8)
	s_waitcnt lgkmcnt(0)
	s_barrier
	s_setprio 1
	s_waitcnt lgkmcnt(0)
	v_mfma_f32_16x16x32_bf16 v[62:65], v[130:133], v[180:183], v[62:65]
	v_mfma_f32_16x16x32_bf16 v[58:61], v[138:141], v[180:183], v[58:61]
	v_mfma_f32_16x16x32_bf16 v[46:49], v[130:133], v[188:191], v[46:49]
	v_mfma_f32_16x16x32_bf16 v[42:45], v[138:141], v[188:191], v[42:45]
	v_mfma_f32_16x16x32_bf16 v[30:33], v[130:133], v[196:199], v[30:33]
	v_mfma_f32_16x16x32_bf16 v[26:29], v[138:141], v[196:199], v[26:29]
	v_mfma_f32_16x16x32_bf16 v[14:17], v[130:133], v[204:207], v[14:17]
	v_mfma_f32_16x16x32_bf16 v[10:13], v[138:141], v[204:207], v[10:13]
	v_mfma_f32_16x16x32_bf16 v[62:65], v[134:137], v[184:187], v[62:65]
	v_mfma_f32_16x16x32_bf16 v[58:61], v[142:145], v[184:187], v[58:61]
	v_mfma_f32_16x16x32_bf16 v[46:49], v[134:137], v[192:195], v[46:49]
	v_mfma_f32_16x16x32_bf16 v[42:45], v[142:145], v[192:195], v[42:45]
	v_mfma_f32_16x16x32_bf16 v[30:33], v[134:137], v[200:203], v[30:33]
	v_mfma_f32_16x16x32_bf16 v[26:29], v[142:145], v[200:203], v[26:29]
	v_mfma_f32_16x16x32_bf16 v[14:17], v[134:137], v[208:211], v[14:17]
	v_mfma_f32_16x16x32_bf16 v[10:13], v[142:145], v[208:211], v[10:13]
	s_setprio 0
	s_setprio 1
	v_mfma_f32_16x16x32_bf16 v[54:57], v[146:149], v[180:183], v[54:57]
	v_mfma_f32_16x16x32_bf16 v[50:53], v[154:157], v[180:183], v[50:53]
	v_mfma_f32_16x16x32_bf16 v[38:41], v[146:149], v[188:191], v[38:41]
	v_mfma_f32_16x16x32_bf16 v[34:37], v[154:157], v[188:191], v[34:37]
	v_mfma_f32_16x16x32_bf16 v[22:25], v[146:149], v[196:199], v[22:25]
	v_mfma_f32_16x16x32_bf16 v[18:21], v[154:157], v[196:199], v[18:21]
	v_mfma_f32_16x16x32_bf16 v[6:9], v[146:149], v[204:207], v[6:9]
	v_mfma_f32_16x16x32_bf16 v[2:5], v[154:157], v[204:207], v[2:5]
	v_mfma_f32_16x16x32_bf16 v[54:57], v[150:153], v[184:187], v[54:57]
	v_mfma_f32_16x16x32_bf16 v[50:53], v[158:161], v[184:187], v[50:53]
	v_mfma_f32_16x16x32_bf16 v[38:41], v[150:153], v[192:195], v[38:41]
	v_mfma_f32_16x16x32_bf16 v[34:37], v[158:161], v[192:195], v[34:37]
	v_mfma_f32_16x16x32_bf16 v[22:25], v[150:153], v[200:203], v[22:25]
	v_mfma_f32_16x16x32_bf16 v[18:21], v[158:161], v[200:203], v[18:21]
	v_mfma_f32_16x16x32_bf16 v[6:9], v[150:153], v[208:211], v[6:9]
	v_mfma_f32_16x16x32_bf16 v[2:5], v[158:161], v[208:211], v[2:5]
	s_setprio 0
	s_barrier
	s_add_i32 s75, 0, 0x18000
	s_add_i32 s88, 0, 0x1c000
	v_add_u32_e32 v142, s75, v242
	s_add_i32 vcc_lo, s100, 0x8000
	v_add_u32_e32 v158, vcc_lo, v242
	ds_read_b128 v[130:133], v142
	ds_read_b128 v[134:137], v142 offset:1024
	ds_read_b128 v[138:141], v142 offset:2048
	ds_read_b128 v[142:145], v142 offset:3072
	ds_read_b128 v[146:149], v158
	ds_read_b128 v[150:153], v158 offset:1024
	ds_read_b128 v[154:157], v158 offset:2048
	ds_read_b128 v[158:161], v158 offset:3072
	s_add_u32 s44, s44, s96
	s_addc_u32 s45, s45, 0
	s_mov_b32 m0, s9
	v_lshl_add_u64 v[224:225], s[44:45], 0, v[164:165]
	ds_read_b128 v[180:183], v243 offset:32768
	ds_read_b128 v[184:187], v243 offset:33792
	ds_read_b128 v[188:191], v243 offset:34816
	ds_read_b128 v[192:195], v243 offset:35840
	ds_read_b128 v[196:199], v243 offset:36864
	ds_read_b128 v[200:203], v243 offset:37888
	ds_read_b128 v[204:207], v243 offset:38912
	ds_read_b128 v[208:211], v243 offset:39936
	global_load_lds_dwordx4 v[224:225], off
	v_lshl_add_u64 v[224:225], s[44:45], 0, v[168:169]
	s_mov_b32 m0, s86
	s_nop 0
	global_load_lds_dwordx4 v[224:225], off
	s_waitcnt vmcnt(8)
	s_waitcnt lgkmcnt(0)
	s_barrier
	s_setprio 1
	s_waitcnt lgkmcnt(0)
	v_mfma_f32_16x16x32_bf16 v[126:129], v[130:133], v[180:183], v[126:129]
	v_mfma_f32_16x16x32_bf16 v[122:125], v[138:141], v[180:183], v[122:125]
	v_mfma_f32_16x16x32_bf16 v[110:113], v[130:133], v[188:191], v[110:113]
	v_mfma_f32_16x16x32_bf16 v[106:109], v[138:141], v[188:191], v[106:109]
	v_mfma_f32_16x16x32_bf16 v[94:97], v[130:133], v[196:199], v[94:97]
	v_mfma_f32_16x16x32_bf16 v[90:93], v[138:141], v[196:199], v[90:93]
	v_mfma_f32_16x16x32_bf16 v[78:81], v[130:133], v[204:207], v[78:81]
	v_mfma_f32_16x16x32_bf16 v[74:77], v[138:141], v[204:207], v[74:77]
	v_mfma_f32_16x16x32_bf16 v[126:129], v[134:137], v[184:187], v[126:129]
	v_mfma_f32_16x16x32_bf16 v[122:125], v[142:145], v[184:187], v[122:125]
	v_mfma_f32_16x16x32_bf16 v[110:113], v[134:137], v[192:195], v[110:113]
	v_mfma_f32_16x16x32_bf16 v[106:109], v[142:145], v[192:195], v[106:109]
	v_mfma_f32_16x16x32_bf16 v[94:97], v[134:137], v[200:203], v[94:97]
	v_mfma_f32_16x16x32_bf16 v[90:93], v[142:145], v[200:203], v[90:93]
	v_mfma_f32_16x16x32_bf16 v[78:81], v[134:137], v[208:211], v[78:81]
	v_mfma_f32_16x16x32_bf16 v[74:77], v[142:145], v[208:211], v[74:77]
	s_setprio 0
	s_setprio 1
	v_mfma_f32_16x16x32_bf16 v[118:121], v[146:149], v[180:183], v[118:121]
	v_mfma_f32_16x16x32_bf16 v[114:117], v[154:157], v[180:183], v[114:117]
	v_mfma_f32_16x16x32_bf16 v[102:105], v[146:149], v[188:191], v[102:105]
	v_mfma_f32_16x16x32_bf16 v[98:101], v[154:157], v[188:191], v[98:101]
	v_mfma_f32_16x16x32_bf16 v[86:89], v[146:149], v[196:199], v[86:89]
	v_mfma_f32_16x16x32_bf16 v[82:85], v[154:157], v[196:199], v[82:85]
	v_mfma_f32_16x16x32_bf16 v[70:73], v[146:149], v[204:207], v[70:73]
	v_mfma_f32_16x16x32_bf16 v[66:69], v[154:157], v[204:207], v[66:69]
	v_mfma_f32_16x16x32_bf16 v[118:121], v[150:153], v[184:187], v[118:121]
	v_mfma_f32_16x16x32_bf16 v[114:117], v[158:161], v[184:187], v[114:117]
	v_mfma_f32_16x16x32_bf16 v[102:105], v[150:153], v[192:195], v[102:105]
	v_mfma_f32_16x16x32_bf16 v[98:101], v[158:161], v[192:195], v[98:101]
	v_mfma_f32_16x16x32_bf16 v[86:89], v[150:153], v[200:203], v[86:89]
	v_mfma_f32_16x16x32_bf16 v[82:85], v[158:161], v[200:203], v[82:85]
	v_mfma_f32_16x16x32_bf16 v[70:73], v[150:153], v[208:211], v[70:73]
	v_mfma_f32_16x16x32_bf16 v[66:69], v[158:161], v[208:211], v[66:69]
	s_setprio 0
	s_barrier
	s_add_i32 s44, s75, s77
	v_lshl_add_u64 v[212:213], v[212:213], 0, s[4:5]
	s_mov_b32 m0, s44
	ds_read_b128 v[180:183], v243 offset:49152
	ds_read_b128 v[184:187], v243 offset:50176
	ds_read_b128 v[188:191], v243 offset:51200
	ds_read_b128 v[192:195], v243 offset:52224
	ds_read_b128 v[196:199], v243 offset:53248
	ds_read_b128 v[200:203], v243 offset:54272
	ds_read_b128 v[204:207], v243 offset:55296
	ds_read_b128 v[208:211], v243 offset:56320
	global_load_lds_dwordx4 v[212:213], off
	v_lshl_add_u64 v[212:213], v[214:215], 0, s[4:5]
	s_add_i32 m0, s44, 0x2000
	s_add_i32 s44, s88, s77
	global_load_lds_dwordx4 v[212:213], off
	v_lshl_add_u64 v[212:213], v[216:217], 0, s[4:5]
	s_mov_b32 m0, s44
	s_nop 0
	global_load_lds_dwordx4 v[212:213], off
	v_lshl_add_u64 v[212:213], v[218:219], 0, s[4:5]
	s_add_i32 m0, s44, 0x2000
	s_nop 0
	global_load_lds_dwordx4 v[212:213], off
	v_lshl_add_u64 v[212:213], v[220:221], 0, s[4:5]
	s_mov_b32 m0, s80
	s_nop 0
	global_load_lds_dwordx4 v[212:213], off
	v_lshl_add_u64 v[212:213], v[222:223], 0, s[4:5]
	s_mov_b32 m0, s84
	s_nop 0
	global_load_lds_dwordx4 v[212:213], off
	s_waitcnt vmcnt(8)
	s_waitcnt lgkmcnt(0)
	s_barrier
	s_setprio 1
	s_waitcnt lgkmcnt(0)
	v_mfma_f32_16x16x32_bf16 v[62:65], v[130:133], v[180:183], v[62:65]
	v_mfma_f32_16x16x32_bf16 v[58:61], v[138:141], v[180:183], v[58:61]
	v_mfma_f32_16x16x32_bf16 v[46:49], v[130:133], v[188:191], v[46:49]
	v_mfma_f32_16x16x32_bf16 v[42:45], v[138:141], v[188:191], v[42:45]
	v_mfma_f32_16x16x32_bf16 v[30:33], v[130:133], v[196:199], v[30:33]
	v_mfma_f32_16x16x32_bf16 v[26:29], v[138:141], v[196:199], v[26:29]
	v_mfma_f32_16x16x32_bf16 v[14:17], v[130:133], v[204:207], v[14:17]
	v_mfma_f32_16x16x32_bf16 v[10:13], v[138:141], v[204:207], v[10:13]
	v_mfma_f32_16x16x32_bf16 v[62:65], v[134:137], v[184:187], v[62:65]
	v_mfma_f32_16x16x32_bf16 v[58:61], v[142:145], v[184:187], v[58:61]
	v_mfma_f32_16x16x32_bf16 v[46:49], v[134:137], v[192:195], v[46:49]
	v_mfma_f32_16x16x32_bf16 v[42:45], v[142:145], v[192:195], v[42:45]
	v_mfma_f32_16x16x32_bf16 v[30:33], v[134:137], v[200:203], v[30:33]
	v_mfma_f32_16x16x32_bf16 v[26:29], v[142:145], v[200:203], v[26:29]
	v_mfma_f32_16x16x32_bf16 v[14:17], v[134:137], v[208:211], v[14:17]
	v_mfma_f32_16x16x32_bf16 v[10:13], v[142:145], v[208:211], v[10:13]
	s_setprio 0
	s_setprio 1
	v_mfma_f32_16x16x32_bf16 v[54:57], v[146:149], v[180:183], v[54:57]
	v_mfma_f32_16x16x32_bf16 v[50:53], v[154:157], v[180:183], v[50:53]
	v_mfma_f32_16x16x32_bf16 v[38:41], v[146:149], v[188:191], v[38:41]
	v_mfma_f32_16x16x32_bf16 v[34:37], v[154:157], v[188:191], v[34:37]
	v_mfma_f32_16x16x32_bf16 v[22:25], v[146:149], v[196:199], v[22:25]
	v_mfma_f32_16x16x32_bf16 v[18:21], v[154:157], v[196:199], v[18:21]
	v_mfma_f32_16x16x32_bf16 v[6:9], v[146:149], v[204:207], v[6:9]
	v_mfma_f32_16x16x32_bf16 v[2:5], v[154:157], v[204:207], v[2:5]
	v_mfma_f32_16x16x32_bf16 v[54:57], v[150:153], v[184:187], v[54:57]
	v_mfma_f32_16x16x32_bf16 v[50:53], v[158:161], v[184:187], v[50:53]
	v_mfma_f32_16x16x32_bf16 v[38:41], v[150:153], v[192:195], v[38:41]
	v_mfma_f32_16x16x32_bf16 v[34:37], v[158:161], v[192:195], v[34:37]
	v_mfma_f32_16x16x32_bf16 v[22:25], v[150:153], v[200:203], v[22:25]
	v_mfma_f32_16x16x32_bf16 v[18:21], v[158:161], v[200:203], v[18:21]
	v_mfma_f32_16x16x32_bf16 v[6:9], v[150:153], v[208:211], v[6:9]
	v_mfma_f32_16x16x32_bf16 v[2:5], v[158:161], v[208:211], v[2:5]
	s_setprio 0
	s_barrier
	s_add_u32 s38, s38, 0x100
	s_addc_u32 s39, s39, 0
	s_add_u32 s56, s56, 0x100
	s_addc_u32 s57, s57, 0
	s_cmp_ge_u32 s74, s83
	s_mov_b32 s44, s74
	s_cbranch_scc0 .LBB0_131
	s_and_b64 vcc, exec, s[30:31]
	s_cbranch_vccz .LBB0_134
	s_barrier

.LBB0_445:
	s_mov_b64 s[8:9], 0x800
	s_mov_b32 s3, 4
.Lsilu_pass:
	global_load_dword v176, v[4:5], off
	v_lshl_add_u64 v[4:5], v[4:5], 0, s[8:9]
	global_load_dword v177, v[4:5], off
	v_lshl_add_u64 v[4:5], v[4:5], 0, s[8:9]
	global_load_dword v178, v[4:5], off
	v_lshl_add_u64 v[4:5], v[4:5], 0, s[8:9]
	global_load_dword v179, v[4:5], off
	v_lshl_add_u64 v[4:5], v[4:5], 0, s[8:9]
	global_load_dword v180, v[4:5], off
	v_lshl_add_u64 v[4:5], v[4:5], 0, s[8:9]
	global_load_dword v181, v[4:5], off
	v_lshl_add_u64 v[4:5], v[4:5], 0, s[8:9]
	global_load_dword v182, v[4:5], off
	v_lshl_add_u64 v[4:5], v[4:5], 0, s[8:9]
	global_load_dword v183, v[4:5], off
	v_lshl_add_u64 v[4:5], v[4:5], 0, s[8:9]
	global_load_dword v184, v[4:5], off
	v_lshl_add_u64 v[4:5], v[4:5], 0, s[8:9]
	global_load_dword v185, v[4:5], off
	v_lshl_add_u64 v[4:5], v[4:5], 0, s[8:9]
	global_load_dword v186, v[4:5], off
	v_lshl_add_u64 v[4:5], v[4:5], 0, s[8:9]
	global_load_dword v187, v[4:5], off
	v_lshl_add_u64 v[4:5], v[4:5], 0, s[8:9]
	global_load_dword v188, v[4:5], off
	v_lshl_add_u64 v[4:5], v[4:5], 0, s[8:9]
	global_load_dword v189, v[4:5], off
	v_lshl_add_u64 v[4:5], v[4:5], 0, s[8:9]
	global_load_dword v190, v[4:5], off
	v_lshl_add_u64 v[4:5], v[4:5], 0, s[8:9]
	global_load_dword v191, v[4:5], off
	v_lshl_add_u64 v[4:5], v[4:5], 0, s[8:9]
	s_waitcnt vmcnt(0)
	v_mul_f32_e32 v192, 0xbfb8aa3b, v176
	v_mul_f32_e32 v193, 0xbfb8aa3b, v177
	v_mul_f32_e32 v194, 0xbfb8aa3b, v178
	v_mul_f32_e32 v195, 0xbfb8aa3b, v179
	v_mul_f32_e32 v196, 0xbfb8aa3b, v180
	v_mul_f32_e32 v197, 0xbfb8aa3b, v181
	v_mul_f32_e32 v198, 0xbfb8aa3b, v182
	v_mul_f32_e32 v199, 0xbfb8aa3b, v183
	v_mul_f32_e32 v200, 0xbfb8aa3b, v184
	v_mul_f32_e32 v201, 0xbfb8aa3b, v185
	v_mul_f32_e32 v202, 0xbfb8aa3b, v186
	v_mul_f32_e32 v203, 0xbfb8aa3b, v187
	v_mul_f32_e32 v204, 0xbfb8aa3b, v188
	v_mul_f32_e32 v205, 0xbfb8aa3b, v189
	v_mul_f32_e32 v206, 0xbfb8aa3b, v190
	v_mul_f32_e32 v207, 0xbfb8aa3b, v191
	v_exp_f32_e32 v192, v192
	v_exp_f32_e32 v193, v193
	v_exp_f32_e32 v194, v194
	v_exp_f32_e32 v195, v195
	v_exp_f32_e32 v196, v196
	v_exp_f32_e32 v197, v197
	v_exp_f32_e32 v198, v198
	v_exp_f32_e32 v199, v199
	v_exp_f32_e32 v200, v200
	v_exp_f32_e32 v201, v201
	v_exp_f32_e32 v202, v202
	v_exp_f32_e32 v203, v203
	v_exp_f32_e32 v204, v204
	v_exp_f32_e32 v205, v205
	v_exp_f32_e32 v206, v206
	v_exp_f32_e32 v207, v207
	v_add_f32_e32 v192, 1.0, v192
	v_add_f32_e32 v193, 1.0, v193
	v_add_f32_e32 v194, 1.0, v194
	v_add_f32_e32 v195, 1.0, v195
	v_add_f32_e32 v196, 1.0, v196
	v_add_f32_e32 v197, 1.0, v197
	v_add_f32_e32 v198, 1.0, v198
	v_add_f32_e32 v199, 1.0, v199
	v_add_f32_e32 v200, 1.0, v200
	v_add_f32_e32 v201, 1.0, v201
	v_add_f32_e32 v202, 1.0, v202
	v_add_f32_e32 v203, 1.0, v203
	v_add_f32_e32 v204, 1.0, v204
	v_add_f32_e32 v205, 1.0, v205
	v_add_f32_e32 v206, 1.0, v206
	v_add_f32_e32 v207, 1.0, v207
	v_rcp_f32_e32 v192, v192
	v_rcp_f32_e32 v193, v193
	v_rcp_f32_e32 v194, v194
	v_rcp_f32_e32 v195, v195
	v_rcp_f32_e32 v196, v196
	v_rcp_f32_e32 v197, v197
	v_rcp_f32_e32 v198, v198
	v_rcp_f32_e32 v199, v199
	v_rcp_f32_e32 v200, v200
	v_rcp_f32_e32 v201, v201
	v_rcp_f32_e32 v202, v202
	v_rcp_f32_e32 v203, v203
	v_rcp_f32_e32 v204, v204
	v_rcp_f32_e32 v205, v205
	v_rcp_f32_e32 v206, v206
	v_rcp_f32_e32 v207, v207
	v_mul_f32_e32 v176, v176, v192
	v_mul_f32_e32 v177, v177, v193
	v_mul_f32_e32 v178, v178, v194
	v_mul_f32_e32 v179, v179, v195
	v_mul_f32_e32 v180, v180, v196
	v_mul_f32_e32 v181, v181, v197
	v_mul_f32_e32 v182, v182, v198
	v_mul_f32_e32 v183, v183, v199
	v_mul_f32_e32 v184, v184, v200
	v_mul_f32_e32 v185, v185, v201
	v_mul_f32_e32 v186, v186, v202
	v_mul_f32_e32 v187, v187, v203
	v_mul_f32_e32 v188, v188, v204
	v_mul_f32_e32 v189, v189, v205
	v_mul_f32_e32 v190, v190, v206
	v_mul_f32_e32 v191, v191, v207
	ds_write_b32 v6, v176
	ds_write_b32 v6, v177 offset:2048
	ds_write_b32 v6, v178 offset:4096
	ds_write_b32 v6, v179 offset:6144
	ds_write_b32 v6, v180 offset:8192
	ds_write_b32 v6, v181 offset:10240
	ds_write_b32 v6, v182 offset:12288
	ds_write_b32 v6, v183 offset:14336
	ds_write_b32 v6, v184 offset:16384
	ds_write_b32 v6, v185 offset:18432
	ds_write_b32 v6, v186 offset:20480
	ds_write_b32 v6, v187 offset:22528
	ds_write_b32 v6, v188 offset:24576
	ds_write_b32 v6, v189 offset:26624
	ds_write_b32 v6, v190 offset:28672
	ds_write_b32 v6, v191 offset:30720
	v_add_u32_e32 v6, 0x8000, v6
	s_sub_u32 s3, s3, 1
	s_cmp_lg_u32 s3, 0
	s_cbranch_scc1 .Lsilu_pass

.LBB0_449:
	v_ashrrev_i32_e32 v9, 31, v8
	v_lshl_add_u64 v[10:11], v[8:9], 2, v[6:7]
	v_add_co_u32_e32 v12, vcc, 0x180000, v10
	s_mov_b32 s3, 0
	s_nop 0
	v_addc_co_u32_e32 v13, vcc, 0, v11, vcc
	v_add_co_u32_e32 v14, vcc, 0x300000, v10
	s_nop 1
	v_addc_co_u32_e32 v15, vcc, 0, v11, vcc
	v_add_co_u32_e32 v22, vcc, 0x480000, v10
	s_nop 1
	v_addc_co_u32_e32 v23, vcc, 0, v11, vcc
	v_add_co_u32_e32 v24, vcc, 0x600000, v10
	s_nop 1
	v_addc_co_u32_e32 v25, vcc, 0, v11, vcc
	v_add_co_u32_e32 v26, vcc, 0x780000, v10
	s_nop 1
	v_addc_co_u32_e32 v27, vcc, 0, v11, vcc
	v_add_co_u32_e32 v28, vcc, 0x900000, v10
	s_nop 1
	v_addc_co_u32_e32 v29, vcc, 0, v11, vcc
	v_add_co_u32_e32 v30, vcc, 0xa80000, v10
	s_nop 1
	v_addc_co_u32_e32 v31, vcc, 0, v11, vcc
	global_load_dword v18, v[10:11], off
	global_load_dword v19, v[12:13], off
	global_load_dword v20, v[14:15], off
	global_load_dword v21, v[22:23], off
	s_nop 0
	global_load_dword v22, v[24:25], off
	global_load_dword v23, v[26:27], off
	s_nop 0
	global_load_dword v24, v[28:29], off
	global_load_dword v25, v[30:31], off
	v_add_co_u32_e32 v12, vcc, 0xc00000, v10
	s_nop 1
	v_addc_co_u32_e32 v13, vcc, 0, v11, vcc
	v_add_co_u32_e32 v14, vcc, 0xd80000, v10
	s_nop 1
	v_addc_co_u32_e32 v15, vcc, 0, v11, vcc
	v_add_co_u32_e32 v28, vcc, 0xf00000, v10
	s_nop 1
	v_addc_co_u32_e32 v29, vcc, 0, v11, vcc
	v_add_co_u32_e32 v30, vcc, 0x1080000, v10
	s_nop 1
	v_addc_co_u32_e32 v31, vcc, 0, v11, vcc
	v_add_co_u32_e32 v32, vcc, 0x1200000, v10
	s_nop 1
	v_addc_co_u32_e32 v33, vcc, 0, v11, vcc
	v_add_co_u32_e32 v34, vcc, 0x1380000, v10
	s_nop 1
	v_addc_co_u32_e32 v35, vcc, 0, v11, vcc
	v_add_co_u32_e32 v36, vcc, 0x1500000, v10
	s_nop 1
	v_addc_co_u32_e32 v37, vcc, 0, v11, vcc
	v_add_co_u32_e32 v38, vcc, 0x1680000, v10
	s_nop 1
	v_addc_co_u32_e32 v39, vcc, 0, v11, vcc
	global_load_dword v26, v[12:13], off
	global_load_dword v27, v[14:15], off
	global_load_dword v10, v[28:29], off
	global_load_dword v11, v[30:31], off
	s_nop 0
	global_load_dword v12, v[32:33], off
	global_load_dword v13, v[34:35], off
	global_load_dword v14, v[36:37], off
	global_load_dword v15, v[38:39], off
	v_mov_b32_e32 v30, 0
	v_mov_b32_e32 v29, v17
	ds_read2st64_b32 v[176:177], v29 offset1:1
	ds_read2st64_b32 v[178:179], v29 offset0:2 offset1:3
	ds_read2st64_b32 v[180:181], v29 offset0:4 offset1:5
	ds_read2st64_b32 v[182:183], v29 offset0:6 offset1:7
	ds_read2st64_b32 v[184:185], v29 offset0:8 offset1:9
	ds_read2st64_b32 v[186:187], v29 offset0:10 offset1:11
	ds_read2st64_b32 v[188:189], v29 offset0:12 offset1:13
	ds_read2st64_b32 v[190:191], v29 offset0:14 offset1:15
	ds_read2st64_b32 v[192:193], v29 offset0:16 offset1:17
	ds_read2st64_b32 v[194:195], v29 offset0:18 offset1:19
	ds_read2st64_b32 v[196:197], v29 offset0:20 offset1:21
	ds_read2st64_b32 v[198:199], v29 offset0:22 offset1:23
	ds_read2st64_b32 v[200:201], v29 offset0:24 offset1:25
	ds_read2st64_b32 v[202:203], v29 offset0:26 offset1:27
	ds_read2st64_b32 v[204:205], v29 offset0:28 offset1:29
	ds_read2st64_b32 v[206:207], v29 offset0:30 offset1:31
	s_waitcnt vmcnt(0)
.Lada_loop:
	s_waitcnt lgkmcnt(8)
	v_mul_f32_e32 v208, v18, v176
	v_mul_f32_e32 v209, v19, v177
	v_fmac_f32_e32 v208, v20, v178
	v_fmac_f32_e32 v209, v21, v179
	v_fmac_f32_e32 v208, v22, v180
	v_fmac_f32_e32 v209, v23, v181
	v_fmac_f32_e32 v208, v24, v182
	v_fmac_f32_e32 v209, v25, v183
	v_fmac_f32_e32 v208, v26, v184
	v_fmac_f32_e32 v209, v27, v185
	v_fmac_f32_e32 v208, v10, v186
	v_fmac_f32_e32 v209, v11, v187
	v_fmac_f32_e32 v208, v12, v188
	v_fmac_f32_e32 v209, v13, v189
	v_fmac_f32_e32 v208, v14, v190
	v_fmac_f32_e32 v209, v15, v191
	s_waitcnt lgkmcnt(0)
	v_mul_f32_e32 v210, v18, v192
	v_mul_f32_e32 v211, v19, v193
	v_fmac_f32_e32 v210, v20, v194
	v_fmac_f32_e32 v211, v21, v195
	v_fmac_f32_e32 v210, v22, v196
	v_fmac_f32_e32 v211, v23, v197
	v_fmac_f32_e32 v210, v24, v198
	v_fmac_f32_e32 v211, v25, v199
	v_fmac_f32_e32 v210, v26, v200
	v_fmac_f32_e32 v211, v27, v201
	v_fmac_f32_e32 v210, v10, v202
	v_fmac_f32_e32 v211, v11, v203
	v_fmac_f32_e32 v210, v12, v204
	v_fmac_f32_e32 v211, v13, v205
	v_fmac_f32_e32 v210, v14, v206
	v_fmac_f32_e32 v211, v15, v207
	v_add_u32_e32 v29, 0x2000, v29
	ds_read2st64_b32 v[176:177], v29 offset1:1
	ds_read2st64_b32 v[178:179], v29 offset0:2 offset1:3
	ds_read2st64_b32 v[180:181], v29 offset0:4 offset1:5
	ds_read2st64_b32 v[182:183], v29 offset0:6 offset1:7
	ds_read2st64_b32 v[184:185], v29 offset0:8 offset1:9
	ds_read2st64_b32 v[186:187], v29 offset0:10 offset1:11
	ds_read2st64_b32 v[188:189], v29 offset0:12 offset1:13
	ds_read2st64_b32 v[190:191], v29 offset0:14 offset1:15
	ds_read2st64_b32 v[192:193], v29 offset0:16 offset1:17
	ds_read2st64_b32 v[194:195], v29 offset0:18 offset1:19
	ds_read2st64_b32 v[196:197], v29 offset0:20 offset1:21
	ds_read2st64_b32 v[198:199], v29 offset0:22 offset1:23
	ds_read2st64_b32 v[200:201], v29 offset0:24 offset1:25
	ds_read2st64_b32 v[202:203], v29 offset0:26 offset1:27
	ds_read2st64_b32 v[204:205], v29 offset0:28 offset1:29
	ds_read2st64_b32 v[206:207], v29 offset0:30 offset1:31
	v_add_f32_e32 v208, v208, v209
	v_add_f32_e32 v210, v210, v211
	s_nop 0
	v_add_f32_dpp v208, v208, v208 quad_perm:[1,0,3,2] row_mask:0xf bank_mask:0xf bound_ctrl:1
	v_add_f32_dpp v210, v210, v210 quad_perm:[1,0,3,2] row_mask:0xf bank_mask:0xf bound_ctrl:1
	s_nop 0
	v_add_f32_dpp v208, v208, v208 quad_perm:[2,3,0,1] row_mask:0xf bank_mask:0xf bound_ctrl:1
	v_add_f32_dpp v210, v210, v210 quad_perm:[2,3,0,1] row_mask:0xf bank_mask:0xf bound_ctrl:1
	s_nop 0
	v_add_f32_dpp v208, v208, v208 row_half_mirror row_mask:0xf bank_mask:0xf bound_ctrl:1
	v_add_f32_dpp v210, v210, v210 row_half_mirror row_mask:0xf bank_mask:0xf bound_ctrl:1
	s_nop 0
	v_add_f32_dpp v208, v208, v208 row_mirror row_mask:0xf bank_mask:0xf bound_ctrl:1
	v_add_f32_dpp v210, v210, v210 row_mirror row_mask:0xf bank_mask:0xf bound_ctrl:1
	s_nop 0
	v_add_f32_dpp v208, v208, v208 row_bcast:15 row_mask:0xa bank_mask:0xf
	v_add_f32_dpp v210, v210, v210 row_bcast:15 row_mask:0xa bank_mask:0xf
	s_nop 0
	v_add_f32_dpp v208, v208, v208 row_bcast:31 row_mask:0xc bank_mask:0xf
	v_add_f32_dpp v210, v210, v210 row_bcast:31 row_mask:0xc bank_mask:0xf
	s_nop 0
	v_readlane_b32 s8, v208, 63
	v_readlane_b32 s9, v210, 63
	s_or_b32 s14, s3, 1
	s_nop 1
	s_mov_b32 m0, s3
	s_nop 0
	v_writelane_b32 v30, s8, m0
	s_mov_b32 m0, s14
	s_nop 0
	v_writelane_b32 v30, s9, m0
	s_add_i32 s3, s3, 2
	s_cmp_lg_u32 s3, 32
	s_cbranch_scc1 .Lada_loop
	s_waitcnt lgkmcnt(0)
	s_and_saveexec_b64 s[14:15], s[40:41]
	s_cbranch_execz .LBB0_448
	v_lshlrev_b64 v[10:11], 2, v[8:9]
	v_lshl_add_u64 v[12:13], s[46:47], 0, v[10:11]
	global_load_dword v9, v[12:13], off
	v_lshl_add_u64 v[10:11], v[4:5], 0, v[10:11]
	s_waitcnt vmcnt(0)
	v_add_f32_e32 v9, v30, v9
	global_store_dword v[10:11], v9, off
	s_branch .LBB0_448
